# S5 pass-1 LDS-DMA u ring; seam: L1 invalidate issued before the release poll (non-leader) and right after L2 writeback (leader)
# speedup vs baseline: 1.0181x; 1.0117x over previous
.LBB0_80:
	s_lshl_b32 s3, s3, 6
	s_add_i32 s4, s3, 0x500
	s_mov_b32 s5, 0
	s_lshl_b64 s[0:1], s[4:5], 2
	s_add_u32 s0, s38, s0
	s_addc_u32 s1, s39, s1
	v_mov_b32_e32 v1, 1
	v_mov_b64_e32 v[4:5], s[0:1]
	flat_atomic_add v1, v[4:5], v1 sc0
	v_cvt_f32_u32_e32 v3, v2
	v_sub_u32_e32 v4, 0, v2
	v_rcp_iflag_f32_e32 v3, v3
	s_nop 0
	v_mul_f32_e32 v3, 0x4f7ffffe, v3
	v_cvt_u32_f32_e32 v3, v3
	v_mul_lo_u32 v4, v4, v3
	v_mul_hi_u32 v4, v3, v4
	v_add_u32_e32 v3, v3, v4
	s_waitcnt vmcnt(0) lgkmcnt(0)
	v_mul_hi_u32 v3, v1, v3
	v_mul_lo_u32 v5, v3, v2
	v_add_u32_e32 v4, 1, v1
	v_sub_u32_e32 v1, v1, v5
	v_add_u32_e32 v6, 1, v3
	v_cmp_ge_u32_e32 vcc, v1, v2
	v_sub_u32_e32 v5, v1, v2
	s_nop 0
	v_cndmask_b32_e32 v3, v3, v6, vcc
	v_cndmask_b32_e32 v1, v1, v5, vcc
	v_add_u32_e32 v5, 1, v3
	v_cmp_ge_u32_e32 vcc, v1, v2
	s_nop 1
	v_cndmask_b32_e32 v1, v3, v5, vcc
	v_mad_u64_u32 v[2:3], s[0:1], v2, v1, v[2:3]
	v_cmp_ne_u32_e32 vcc, v4, v2
	s_and_saveexec_b64 s[0:1], vcc
	s_xor_b64 s[0:1], exec, s[0:1]
	s_cbranch_execz .LBB0_93
	buffer_inv sc1
	s_add_i32 s4, s3, 0x900
	s_lshl_b64 s[4:5], s[4:5], 2
	s_add_u32 s6, s38, s4
	s_addc_u32 s7, s39, s5
	v_mov_b64_e32 v[2:3], s[6:7]
	flat_load_dword v0, v[2:3] sc1
	s_waitcnt vmcnt(0) lgkmcnt(0)
	v_cmp_eq_u32_e32 vcc, v0, v1
	s_and_saveexec_b64 s[4:5], vcc
	s_cbranch_execz .LBB0_92
	s_mov_b32 s22, 1
	s_mov_b64 s[8:9], 0
	s_branch .LBB0_84

.LBB0_92:
	s_or_b64 exec, exec, s[4:5]
	s_waitcnt vmcnt(0) lgkmcnt(0)
	s_nop 0
	s_waitcnt vmcnt(0)
.LBB0_93:
	s_andn2_saveexec_b64 s[0:1], s[0:1]
	s_cbranch_execz .LBB0_109
	v_mov_b32_e32 v1, s38
	v_add_co_u32_e32 v2, vcc, 0x3000, v1
	v_mov_b32_e32 v1, s39
	buffer_wbl2 sc1
	s_waitcnt vmcnt(0)
	buffer_inv sc1
	v_addc_co_u32_e32 v3, vcc, 0, v1, vcc
	v_mov_b32_e32 v1, 1
	flat_atomic_add v1, v[2:3], v1 offset:1024 sc0
	v_cvt_f32_u32_e32 v2, v0
	v_sub_u32_e32 v3, 0, v0
	s_add_u32 s0, s38, 0x3500
	s_addc_u32 s1, s39, 0
	v_rcp_iflag_f32_e32 v2, v2
	s_mov_b64 s[6:7], -1
	v_mul_f32_e32 v2, 0x4f7ffffe, v2
	v_cvt_u32_f32_e32 v2, v2
	v_mul_lo_u32 v3, v3, v2
	v_mul_hi_u32 v3, v2, v3
	v_add_u32_e32 v2, v2, v3
	s_waitcnt vmcnt(0) lgkmcnt(0)
	v_mul_hi_u32 v2, v1, v2
	v_mul_lo_u32 v4, v2, v0
	v_add_u32_e32 v3, 1, v1
	v_sub_u32_e32 v1, v1, v4
	v_add_u32_e32 v5, 1, v2
	v_cmp_ge_u32_e32 vcc, v1, v0
	v_sub_u32_e32 v4, v1, v0
	s_nop 0
	v_cndmask_b32_e32 v2, v2, v5, vcc
	v_cndmask_b32_e32 v1, v1, v4, vcc
	v_add_u32_e32 v4, 1, v2
	v_cmp_ge_u32_e32 vcc, v1, v0
	s_nop 1
	v_cndmask_b32_e32 v2, v2, v4, vcc
	v_mad_u64_u32 v[0:1], s[4:5], v0, v2, v[0:1]
	v_cmp_ne_u32_e32 vcc, v3, v0
	v_mov_b64_e32 v[0:1], s[0:1]
	s_and_saveexec_b64 s[4:5], vcc
	s_cbranch_execz .LBB0_106
	v_mov_b64_e32 v[0:1], s[0:1]
	flat_load_dword v0, v[0:1] sc1
	s_mov_b64 s[10:11], 0
	s_waitcnt vmcnt(0) lgkmcnt(0)
	v_cmp_eq_u32_e32 vcc, v0, v2
	s_and_saveexec_b64 s[8:9], vcc
	s_cbranch_execz .LBB0_105
	s_add_u32 s6, s38, 0x200
	s_addc_u32 s7, s39, 0
	s_mov_b32 s22, 1
	s_branch .LBB0_98

.LBB0_108:
	s_or_b64 exec, exec, s[0:1]
	s_add_i32 s0, s3, 0x900
	s_mov_b32 s1, 0
	s_lshl_b64 s[0:1], s[0:1], 2
	s_add_u32 s0, s38, s0
	s_addc_u32 s1, s39, s1
	v_mov_b32_e32 v2, 1
	v_mov_b64_e32 v[0:1], s[0:1]
	s_waitcnt vmcnt(0) lgkmcnt(0)
	s_nop 0
	flat_atomic_add v[0:1], v2
	s_waitcnt vmcnt(0)

.LBB0_250:
	s_lshl_b32 s20, s33, 6
	s_add_i32 s2, s20, 0x500
	s_mov_b32 s3, 0
	s_lshl_b64 s[0:1], s[2:3], 2
	s_add_u32 s0, s36, s0
	s_addc_u32 s1, s37, s1
	v_mov_b32_e32 v1, 1
	v_mov_b64_e32 v[4:5], s[0:1]
	flat_atomic_add v1, v[4:5], v1 sc0
	v_cvt_f32_u32_e32 v3, v2
	v_sub_u32_e32 v4, 0, v2
	v_rcp_iflag_f32_e32 v3, v3
	s_nop 0
	v_mul_f32_e32 v3, 0x4f7ffffe, v3
	v_cvt_u32_f32_e32 v3, v3
	v_mul_lo_u32 v4, v4, v3
	v_mul_hi_u32 v4, v3, v4
	v_add_u32_e32 v3, v3, v4
	s_waitcnt vmcnt(0) lgkmcnt(0)
	v_mul_hi_u32 v3, v1, v3
	v_mul_lo_u32 v5, v3, v2
	v_add_u32_e32 v4, 1, v1
	v_sub_u32_e32 v1, v1, v5
	v_add_u32_e32 v6, 1, v3
	v_cmp_ge_u32_e32 vcc, v1, v2
	v_sub_u32_e32 v5, v1, v2
	s_nop 0
	v_cndmask_b32_e32 v3, v3, v6, vcc
	v_cndmask_b32_e32 v1, v1, v5, vcc
	v_add_u32_e32 v5, 1, v3
	v_cmp_ge_u32_e32 vcc, v1, v2
	s_nop 1
	v_cndmask_b32_e32 v1, v3, v5, vcc
	v_mad_u64_u32 v[2:3], s[0:1], v2, v1, v[2:3]
	v_cmp_ne_u32_e32 vcc, v4, v2
	s_and_saveexec_b64 s[0:1], vcc
	s_xor_b64 s[0:1], exec, s[0:1]
	s_cbranch_execz .LBB0_263
	buffer_inv sc1
	s_add_i32 s2, s20, 0x900
	s_lshl_b64 s[2:3], s[2:3], 2
	s_add_u32 s4, s36, s2
	s_addc_u32 s5, s37, s3
	v_mov_b64_e32 v[2:3], s[4:5]
	flat_load_dword v0, v[2:3] sc1
	s_waitcnt vmcnt(0) lgkmcnt(0)
	v_cmp_eq_u32_e32 vcc, v0, v1
	s_and_saveexec_b64 s[2:3], vcc
	s_cbranch_execz .LBB0_262
	s_mov_b32 s21, 1
	s_mov_b64 s[6:7], 0
	s_branch .LBB0_254

.LBB0_262:
	s_or_b64 exec, exec, s[2:3]
	s_waitcnt vmcnt(0) lgkmcnt(0)
	s_nop 0
	s_waitcnt vmcnt(0)
.LBB0_263:
	s_andn2_saveexec_b64 s[0:1], s[0:1]
	s_cbranch_execz .LBB0_279
	v_mov_b32_e32 v1, s36
	v_add_co_u32_e32 v2, vcc, 0x3000, v1
	v_mov_b32_e32 v1, s37
	buffer_wbl2 sc1
	s_waitcnt vmcnt(0)
	buffer_inv sc1
	v_addc_co_u32_e32 v3, vcc, 0, v1, vcc
	v_mov_b32_e32 v1, 1
	flat_atomic_add v1, v[2:3], v1 offset:1024 sc0
	v_cvt_f32_u32_e32 v2, v0
	v_sub_u32_e32 v3, 0, v0
	s_mov_b64 s[4:5], -1
	v_rcp_iflag_f32_e32 v2, v2
	s_nop 0
	v_mul_f32_e32 v2, 0x4f7ffffe, v2
	v_cvt_u32_f32_e32 v2, v2
	v_mul_lo_u32 v3, v3, v2
	v_mul_hi_u32 v3, v2, v3
	v_add_u32_e32 v2, v2, v3
	s_waitcnt vmcnt(0) lgkmcnt(0)
	v_mul_hi_u32 v2, v1, v2
	v_mul_lo_u32 v3, v2, v0
	v_sub_u32_e32 v3, v1, v3
	v_cmp_ge_u32_e32 vcc, v3, v0
	v_add_u32_e32 v4, 1, v2
	s_nop 0
	v_cndmask_b32_e32 v2, v2, v4, vcc
	v_sub_u32_e32 v4, v3, v0
	v_cndmask_b32_e32 v3, v3, v4, vcc
	v_cmp_ge_u32_e32 vcc, v3, v0
	v_add_u32_e32 v3, 1, v2
	s_nop 0
	v_cndmask_b32_e32 v2, v2, v3, vcc
	v_add_u32_e32 v3, 1, v1
	v_mad_u64_u32 v[0:1], s[0:1], v0, v2, v[0:1]
	s_add_u32 s0, s36, 0x3500
	s_addc_u32 s1, s37, 0
	v_cmp_ne_u32_e32 vcc, v3, v0
	v_mov_b64_e32 v[0:1], s[0:1]
	s_and_saveexec_b64 s[2:3], vcc
	s_cbranch_execz .LBB0_276
	v_mov_b64_e32 v[0:1], s[0:1]
	flat_load_dword v0, v[0:1] sc1
	s_mov_b64 s[8:9], 0
	s_waitcnt vmcnt(0) lgkmcnt(0)
	v_cmp_eq_u32_e32 vcc, v0, v2
	s_and_saveexec_b64 s[6:7], vcc
	s_cbranch_execz .LBB0_275
	s_add_u32 s4, s36, 0x200
	s_addc_u32 s5, s37, 0
	s_mov_b32 s21, 1
	s_branch .LBB0_268

.LBB0_278:
	s_or_b64 exec, exec, s[0:1]
	s_add_i32 s0, s20, 0x900
	s_mov_b32 s1, 0
	s_lshl_b64 s[0:1], s[0:1], 2
	s_add_u32 s0, s36, s0
	s_addc_u32 s1, s37, s1
	v_mov_b32_e32 v2, 1
	v_mov_b64_e32 v[0:1], s[0:1]
	s_waitcnt vmcnt(0) lgkmcnt(0)
	s_nop 0
	flat_atomic_add v[0:1], v2
	s_waitcnt vmcnt(0)

.LBB0_530:
	s_lshl_b32 s20, s33, 6
	s_add_i32 s2, s20, 0x500
	s_mov_b32 s3, 0
	s_lshl_b64 s[0:1], s[2:3], 2
	s_add_u32 s0, s36, s0
	s_addc_u32 s1, s37, s1
	v_mov_b32_e32 v1, 1
	v_mov_b64_e32 v[4:5], s[0:1]
	flat_atomic_add v3, v[4:5], v1 sc0
	v_cvt_f32_u32_e32 v1, v2
	v_sub_u32_e32 v4, 0, v2
	v_rcp_iflag_f32_e32 v1, v1
	s_nop 0
	v_mul_f32_e32 v1, 0x4f7ffffe, v1
	v_cvt_u32_f32_e32 v1, v1
	v_mul_lo_u32 v4, v4, v1
	v_mul_hi_u32 v4, v1, v4
	v_add_u32_e32 v1, v1, v4
	s_waitcnt vmcnt(0) lgkmcnt(0)
	v_mul_hi_u32 v1, v3, v1
	v_mul_lo_u32 v4, v1, v2
	v_sub_u32_e32 v4, v3, v4
	v_cmp_ge_u32_e32 vcc, v4, v2
	v_add_u32_e32 v5, 1, v1
	s_nop 0
	v_cndmask_b32_e32 v1, v1, v5, vcc
	v_sub_u32_e32 v5, v4, v2
	v_cndmask_b32_e32 v4, v4, v5, vcc
	v_cmp_ge_u32_e32 vcc, v4, v2
	v_add_u32_e32 v4, 1, v1
	s_nop 0
	v_cndmask_b32_e32 v1, v1, v4, vcc
	v_add_u32_e32 v4, 1, v3
	v_mad_u64_u32 v[2:3], s[0:1], v2, v1, v[2:3]
	v_cmp_ne_u32_e32 vcc, v4, v2
	s_and_saveexec_b64 s[0:1], vcc
	s_xor_b64 s[0:1], exec, s[0:1]
	s_cbranch_execz .LBB0_543
	buffer_inv sc1
	s_add_i32 s2, s20, 0x900
	s_lshl_b64 s[2:3], s[2:3], 2
	s_add_u32 s4, s36, s2
	s_addc_u32 s5, s37, s3
	v_mov_b64_e32 v[2:3], s[4:5]
	flat_load_dword v0, v[2:3] sc1
	s_waitcnt vmcnt(0) lgkmcnt(0)
	v_cmp_eq_u32_e32 vcc, v0, v1
	s_and_saveexec_b64 s[2:3], vcc
	s_cbranch_execz .LBB0_542
	s_mov_b32 s21, 1
	s_mov_b64 s[6:7], 0
	s_branch .LBB0_534

.LBB0_976:
	s_or_b64 exec, exec, s[2:3]
	s_add_i32 s0, s10, 0x100
	s_lshl_b32 s2, s9, 1
	s_add_u32 s2, s76, s2
	v_mov_b32_e32 v38, s30
	s_movk_i32 s9, 0x210
	s_addc_u32 s3, s77, 0
	v_mad_u32_u24 v38, v43, s9, v38
	v_and_b32_e32 v39, -16, v42
	v_mov_b32_e32 v50, 0
	v_lshl_add_u64 v[48:49], v[36:37], 1, s[2:3]
	v_lshl_add_u32 v40, v42, 2, s30
	s_waitcnt vmcnt(0)
	v_mov_b32_e32 v45, v44
	v_mov_b32_e32 v47, v46
	v_add_u32_e32 v52, v38, v39
	v_mov_b32_e32 v51, v50
	s_mov_b32 s98, 0
	s_and_saveexec_b64 s[2:3], vcc
	s_mov_b32 s99, s10
	v_or_b32_e32 v36, s99, v43
	v_mad_i64_i32 v[36:37], s[100:101], v36, s4, v[48:49]
	s_add_i32 m0, s30, 0x2100
	s_nop 0
	global_load_lds_dwordx4 v[36:37], off
	s_add_i32 s99, s10, 16
	v_or_b32_e32 v36, s99, v43
	v_mad_i64_i32 v[36:37], s[100:101], v36, s4, v[48:49]
	s_add_i32 m0, s30, 0x2300
	s_nop 0
	global_load_lds_dwordx4 v[36:37], off
	s_add_i32 s99, s10, 32
	v_or_b32_e32 v36, s99, v43
	v_mad_i64_i32 v[36:37], s[100:101], v36, s4, v[48:49]
	s_add_i32 m0, s30, 0x2500
	s_nop 0
	global_load_lds_dwordx4 v[36:37], off
	s_add_i32 s99, s10, 48
	v_or_b32_e32 v36, s99, v43
	v_mad_i64_i32 v[36:37], s[100:101], v36, s4, v[48:49]
	s_add_i32 m0, s30, 0x2700
	s_nop 0
	global_load_lds_dwordx4 v[36:37], off
	s_add_i32 s99, s10, 64
	v_or_b32_e32 v36, s99, v43
	v_mad_i64_i32 v[36:37], s[100:101], v36, s4, v[48:49]
	s_add_i32 m0, s30, 0x2900
	s_nop 0
	global_load_lds_dwordx4 v[36:37], off
	s_add_i32 s99, s10, 80
	v_or_b32_e32 v36, s99, v43
	v_mad_i64_i32 v[36:37], s[100:101], v36, s4, v[48:49]
	s_add_i32 m0, s30, 0x2b00
	s_nop 0
	global_load_lds_dwordx4 v[36:37], off
	s_add_i32 s99, s10, 96
	v_or_b32_e32 v36, s99, v43
	v_mad_i64_i32 v[36:37], s[100:101], v36, s4, v[48:49]
	s_add_i32 m0, s30, 0x2d00
	s_nop 0
	global_load_lds_dwordx4 v[36:37], off
	s_add_i32 s99, s10, 112
	v_or_b32_e32 v36, s99, v43
	v_mad_i64_i32 v[36:37], s[100:101], v36, s4, v[48:49]
	s_add_i32 m0, s30, 0x2f00
	s_nop 0
	global_load_lds_dwordx4 v[36:37], off
	s_or_b64 exec, exec, s[2:3]
	s_branch .LBB0_978
.LBB0_977:
	s_or_b64 exec, exec, s[2:3]
	v_mfma_f32_16x16x32_bf16 v[54:57], v[0:3], v[32:35], 0
	v_add_u32_e32 v53, 32, v40
	s_cmp_lt_i32 s9, s0
	s_mov_b32 s10, s9
	v_mfma_f32_16x16x32_bf16 v[58:61], v[8:11], v[32:35], 0
	v_mfma_f32_16x16x32_bf16 v[62:65], v[4:7], v[32:35], 0
	s_nop 2
	ds_write_b128 v52, v[54:57]
	v_mfma_f32_16x16x32_bf16 v[66:69], v[16:19], v[32:35], 0
	s_nop 1
	ds_write_b128 v52, v[58:61] offset:64
	ds_write_b128 v52, v[62:65] offset:128
	s_nop 3
	ds_write_b128 v52, v[66:69] offset:192
	v_mfma_f32_16x16x32_bf16 v[70:73], v[12:15], v[32:35], 0
	v_mfma_f32_16x16x32_bf16 v[54:57], v[24:27], v[32:35], 0
	v_mfma_f32_16x16x32_bf16 v[58:61], v[20:23], v[32:35], 0
	s_nop 5
	ds_write_b128 v52, v[70:73] offset:256
	ds_write_b128 v52, v[54:57] offset:320
	ds_write_b128 v52, v[58:61] offset:384
	v_mfma_f32_16x16x32_bf16 v[32:35], v[28:31], v[32:35], 0
	s_nop 7
	ds_write_b128 v52, v[32:35] offset:448
	s_waitcnt lgkmcnt(0)
	ds_read2st64_b32 v[32:33], v40 offset1:1
	ds_read2_b32 v[34:35], v40 offset0:132 offset1:196
	ds_read2st64_b32 v[54:55], v53 offset0:4 offset1:5
	v_add_u32_e32 v53, 48, v40
	ds_read2st64_b32 v[56:57], v53 offset0:6 offset1:7
	v_add_u32_e32 v53, 64, v40
	ds_read2st64_b32 v[58:59], v53 offset0:8 offset1:9
	v_add_u32_e32 v53, 0x50, v40
	ds_read2st64_b32 v[60:61], v53 offset0:10 offset1:11
	v_add_u32_e32 v53, 0x60, v40
	ds_read2st64_b32 v[62:63], v53 offset0:12 offset1:13
	v_add_u32_e32 v53, 0x70, v40
	ds_read2st64_b32 v[64:65], v53 offset0:14 offset1:15
	v_add_u32_e32 v53, 0x80, v40
	ds_read2st64_b32 v[66:67], v53 offset0:16 offset1:17
	v_add_u32_e32 v53, 0x90, v40
	ds_read2st64_b32 v[68:69], v53 offset0:18 offset1:19
	v_add_u32_e32 v53, 0xa0, v40
	ds_read2st64_b32 v[70:71], v53 offset0:20 offset1:21
	v_add_u32_e32 v53, 0xb0, v40
	ds_read2st64_b32 v[72:73], v53 offset0:22 offset1:23
	v_add_u32_e32 v53, 0xc0, v40
	ds_read2st64_b32 v[74:75], v53 offset0:24 offset1:25
	v_add_u32_e32 v53, 0xd0, v40
	ds_read2st64_b32 v[76:77], v53 offset0:26 offset1:27
	v_add_u32_e32 v53, 0xe0, v40
	ds_read2st64_b32 v[78:79], v53 offset0:28 offset1:29
	v_add_u32_e32 v53, 0xf0, v40
	ds_read2st64_b32 v[80:81], v53 offset0:30 offset1:31
	v_mul_f32_e32 v53, v46, v51
	v_mul_f32_e32 v51, v44, v51
	v_fmac_f32_e32 v51, v46, v50
	v_fma_f32 v53, v44, v50, -v53
	s_waitcnt lgkmcnt(14)
	v_add_f32_e32 v33, v51, v33
	v_add_f32_e32 v32, v53, v32
	v_mul_f32_e32 v50, v46, v33
	v_mul_f32_e32 v33, v44, v33
	v_fmac_f32_e32 v33, v46, v32
	v_fma_f32 v50, v44, v32, -v50
	v_add_f32_e32 v32, v35, v33
	v_add_f32_e32 v34, v34, v50
	v_mul_f32_e32 v33, v46, v32
	v_fma_f32 v33, v44, v34, -v33
	v_mul_f32_e32 v34, v46, v34
	v_fmac_f32_e32 v34, v44, v32
	s_waitcnt lgkmcnt(13)
	v_add_f32_e32 v32, v55, v34
	v_add_f32_e32 v33, v54, v33
	v_mul_f32_e32 v34, v46, v32
	v_fma_f32 v34, v44, v33, -v34
	v_mul_f32_e32 v33, v46, v33
	v_fmac_f32_e32 v33, v44, v32
	s_waitcnt lgkmcnt(12)
	v_add_f32_e32 v32, v57, v33
	v_add_f32_e32 v34, v56, v34
	v_mul_f32_e32 v33, v46, v32
	v_fma_f32 v33, v44, v34, -v33
	v_mul_f32_e32 v34, v46, v34
	v_fmac_f32_e32 v34, v44, v32
	s_waitcnt lgkmcnt(11)
	v_add_f32_e32 v32, v59, v34
	v_add_f32_e32 v33, v58, v33
	v_mul_f32_e32 v34, v46, v32
	v_fma_f32 v34, v44, v33, -v34
	v_mul_f32_e32 v33, v46, v33
	v_fmac_f32_e32 v33, v44, v32
	s_waitcnt lgkmcnt(10)
	v_add_f32_e32 v32, v61, v33
	v_add_f32_e32 v34, v60, v34
	v_mul_f32_e32 v33, v46, v32
	v_fma_f32 v33, v44, v34, -v33
	v_mul_f32_e32 v34, v46, v34
	v_fmac_f32_e32 v34, v44, v32
	s_waitcnt lgkmcnt(9)
	v_add_f32_e32 v32, v63, v34
	v_add_f32_e32 v33, v62, v33
	v_mul_f32_e32 v34, v46, v32
	v_fma_f32 v34, v44, v33, -v34
	v_mul_f32_e32 v33, v46, v33
	v_fmac_f32_e32 v33, v44, v32
	s_waitcnt lgkmcnt(8)
	v_add_f32_e32 v32, v65, v33
	v_add_f32_e32 v34, v64, v34
	v_mul_f32_e32 v33, v46, v32
	v_fma_f32 v33, v44, v34, -v33
	v_mul_f32_e32 v34, v46, v34
	v_fmac_f32_e32 v34, v44, v32
	s_waitcnt lgkmcnt(7)
	v_add_f32_e32 v32, v67, v34
	v_add_f32_e32 v33, v66, v33
	v_mul_f32_e32 v34, v46, v32
	v_fma_f32 v34, v44, v33, -v34
	v_mul_f32_e32 v33, v46, v33
	v_fmac_f32_e32 v33, v44, v32
	s_waitcnt lgkmcnt(6)
	v_add_f32_e32 v32, v69, v33
	v_add_f32_e32 v34, v68, v34
	v_mul_f32_e32 v33, v46, v32
	v_fma_f32 v33, v44, v34, -v33
	v_mul_f32_e32 v34, v46, v34
	v_fmac_f32_e32 v34, v44, v32
	s_waitcnt lgkmcnt(5)
	v_add_f32_e32 v32, v71, v34
	v_add_f32_e32 v33, v70, v33
	v_mul_f32_e32 v34, v46, v32
	v_fma_f32 v34, v44, v33, -v34
	v_mul_f32_e32 v33, v46, v33
	v_fmac_f32_e32 v33, v44, v32
	s_waitcnt lgkmcnt(4)
	v_add_f32_e32 v34, v72, v34
	v_add_f32_e32 v35, v73, v33
	v_mul_f32_e32 v32, v46, v35
	v_mul_f32_e32 v33, v46, v34
	v_fma_f32 v32, v44, v34, -v32
	v_fmac_f32_e32 v33, v44, v35
	s_waitcnt lgkmcnt(3)
	v_pk_add_f32 v[32:33], v[74:75], v[32:33]
	s_waitcnt lgkmcnt(0)
	s_nop 0
	v_pk_mul_f32 v[34:35], v[46:47], v[32:33]
	s_nop 0
	v_pk_fma_f32 v[50:51], v[44:45], v[32:33], v[34:35] op_sel:[0,0,1] op_sel_hi:[1,1,0] neg_lo:[0,0,1] neg_hi:[0,0,1]
	v_pk_fma_f32 v[32:33], v[44:45], v[32:33], v[34:35] op_sel:[0,0,1] op_sel_hi:[1,1,0]
	s_nop 0
	v_mov_b32_e32 v51, v33
	s_waitcnt lgkmcnt(2)
	v_pk_add_f32 v[32:33], v[76:77], v[50:51]
	s_nop 0
	v_pk_mul_f32 v[34:35], v[46:47], v[32:33]
	s_nop 0
	v_pk_fma_f32 v[50:51], v[44:45], v[32:33], v[34:35] op_sel:[0,0,1] op_sel_hi:[1,1,0] neg_lo:[0,0,1] neg_hi:[0,0,1]
	v_pk_fma_f32 v[32:33], v[44:45], v[32:33], v[34:35] op_sel:[0,0,1] op_sel_hi:[1,1,0]
	s_nop 0
	v_mov_b32_e32 v51, v33
	s_waitcnt lgkmcnt(1)
	v_pk_add_f32 v[32:33], v[78:79], v[50:51]
	s_nop 0
	v_pk_mul_f32 v[34:35], v[46:47], v[32:33]
	s_nop 0
	v_pk_fma_f32 v[50:51], v[44:45], v[32:33], v[34:35] op_sel:[0,0,1] op_sel_hi:[1,1,0] neg_lo:[0,0,1] neg_hi:[0,0,1]
	v_pk_fma_f32 v[32:33], v[44:45], v[32:33], v[34:35] op_sel:[0,0,1] op_sel_hi:[1,1,0]
	s_nop 0
	v_mov_b32_e32 v34, v38
	v_mov_b32_e32 v51, v33
	s_waitcnt lgkmcnt(0)
	v_pk_add_f32 v[50:51], v[80:81], v[50:51]
	v_mov_b32_e32 v32, v36
	v_mov_b32_e32 v33, v37
	v_mov_b32_e32 v35, v39
	s_cbranch_scc0 .LBB0_957
.LBB0_978:
	s_add_i32 s9, s10, 16
	v_mov_b32_e32 v36, 0
	v_mov_b32_e32 v37, 0
	v_mov_b32_e32 v38, 0
	v_mov_b32_e32 v39, 0
	s_and_saveexec_b64 s[2:3], vcc
	s_cbranch_execz .LBB0_977
	s_add_i32 s99, s10, 0x80
	s_add_i32 s100, s0, -16
	s_min_i32 s99, s99, s100
	v_or_b32_e32 v36, s99, v43
	s_add_i32 s99, s30, 0x2100
	v_mad_i64_i32 v[36:37], s[100:101], v36, s4, v[48:49]
	s_add_i32 m0, s99, s98
	s_add_i32 s98, s98, 0x200
	s_and_b32 s98, s98, 0xfff
	global_load_lds_dwordx4 v[36:37], off
	s_add_i32 s99, s99, s98
	v_lshl_add_u32 v38, v42, 4, s99
	s_waitcnt vmcnt(7)
	ds_read_b128 v[36:39], v38
	s_branch .LBB0_977

.LBB0_1037:
	s_lshl_b32 s20, s33, 6
	s_add_i32 s2, s20, 0x500
	s_mov_b32 s3, 0
	s_lshl_b64 s[0:1], s[2:3], 2
	s_add_u32 s0, s34, s0
	s_addc_u32 s1, s35, s1
	v_mov_b32_e32 v1, 1
	v_mov_b64_e32 v[4:5], s[0:1]
	flat_atomic_add v3, v[4:5], v1 sc0
	v_cvt_f32_u32_e32 v1, v2
	v_sub_u32_e32 v4, 0, v2
	v_rcp_iflag_f32_e32 v1, v1
	s_nop 0
	v_mul_f32_e32 v1, 0x4f7ffffe, v1
	v_cvt_u32_f32_e32 v1, v1
	v_mul_lo_u32 v4, v4, v1
	v_mul_hi_u32 v4, v1, v4
	v_add_u32_e32 v1, v1, v4
	s_waitcnt vmcnt(0) lgkmcnt(0)
	v_mul_hi_u32 v1, v3, v1
	v_mul_lo_u32 v4, v1, v2
	v_sub_u32_e32 v4, v3, v4
	v_cmp_ge_u32_e32 vcc, v4, v2
	v_add_u32_e32 v5, 1, v1
	s_nop 0
	v_cndmask_b32_e32 v1, v1, v5, vcc
	v_sub_u32_e32 v5, v4, v2
	v_cndmask_b32_e32 v4, v4, v5, vcc
	v_cmp_ge_u32_e32 vcc, v4, v2
	v_add_u32_e32 v4, 1, v1
	s_nop 0
	v_cndmask_b32_e32 v1, v1, v4, vcc
	v_add_u32_e32 v4, 1, v3
	v_mad_u64_u32 v[2:3], s[0:1], v2, v1, v[2:3]
	v_cmp_ne_u32_e32 vcc, v4, v2
	s_and_saveexec_b64 s[0:1], vcc
	s_xor_b64 s[0:1], exec, s[0:1]
	s_cbranch_execz .LBB0_1050
	buffer_inv sc1
	s_add_i32 s2, s20, 0x900
	s_lshl_b64 s[2:3], s[2:3], 2
	s_add_u32 s4, s34, s2
	s_addc_u32 s5, s35, s3
	v_mov_b64_e32 v[2:3], s[4:5]
	flat_load_dword v0, v[2:3] sc1
	s_waitcnt vmcnt(0) lgkmcnt(0)
	v_cmp_eq_u32_e32 vcc, v0, v1
	s_and_saveexec_b64 s[2:3], vcc
	s_cbranch_execz .LBB0_1049
	s_mov_b32 s21, 1
	s_mov_b64 s[6:7], 0
	s_branch .LBB0_1041

.LBB0_1050:
	s_andn2_saveexec_b64 s[0:1], s[0:1]
	s_cbranch_execz .LBB0_1066
	v_mov_b32_e32 v1, s34
	v_add_co_u32_e32 v2, vcc, 0x3000, v1
	v_mov_b32_e32 v1, s35
	buffer_wbl2 sc1
	s_waitcnt vmcnt(0)
	buffer_inv sc1
	v_addc_co_u32_e32 v3, vcc, 0, v1, vcc
	v_mov_b32_e32 v1, 1
	flat_atomic_add v1, v[2:3], v1 offset:1024 sc0
	v_cvt_f32_u32_e32 v2, v0
	v_sub_u32_e32 v3, 0, v0
	s_mov_b64 s[4:5], -1
	v_rcp_iflag_f32_e32 v2, v2
	s_nop 0
	v_mul_f32_e32 v2, 0x4f7ffffe, v2
	v_cvt_u32_f32_e32 v2, v2
	v_mul_lo_u32 v3, v3, v2
	v_mul_hi_u32 v3, v2, v3
	v_add_u32_e32 v2, v2, v3
	s_waitcnt vmcnt(0) lgkmcnt(0)
	v_mul_hi_u32 v2, v1, v2
	v_mul_lo_u32 v3, v2, v0
	v_sub_u32_e32 v3, v1, v3
	v_cmp_ge_u32_e32 vcc, v3, v0
	v_add_u32_e32 v4, 1, v2
	s_nop 0
	v_cndmask_b32_e32 v2, v2, v4, vcc
	v_sub_u32_e32 v4, v3, v0
	v_cndmask_b32_e32 v3, v3, v4, vcc
	v_cmp_ge_u32_e32 vcc, v3, v0
	v_add_u32_e32 v3, 1, v2
	s_nop 0
	v_cndmask_b32_e32 v2, v2, v3, vcc
	v_add_u32_e32 v3, 1, v1
	v_mad_u64_u32 v[0:1], s[0:1], v0, v2, v[0:1]
	s_add_u32 s0, s34, 0x3500
	s_addc_u32 s1, s35, 0
	v_cmp_ne_u32_e32 vcc, v3, v0
	v_mov_b64_e32 v[0:1], s[0:1]
	s_and_saveexec_b64 s[2:3], vcc
	s_cbranch_execz .LBB0_1063
	v_mov_b64_e32 v[0:1], s[0:1]
	flat_load_dword v0, v[0:1] sc1
	s_mov_b64 s[8:9], 0
	s_waitcnt vmcnt(0) lgkmcnt(0)
	v_cmp_eq_u32_e32 vcc, v0, v2
	s_and_saveexec_b64 s[6:7], vcc
	s_cbranch_execz .LBB0_1062
	s_add_u32 s4, s34, 0x200
	s_addc_u32 s5, s35, 0
	s_mov_b32 s21, 1
	s_branch .LBB0_1055

.LBB0_1065:
	s_or_b64 exec, exec, s[0:1]
	s_add_i32 s0, s20, 0x900
	s_mov_b32 s1, 0
	s_lshl_b64 s[0:1], s[0:1], 2
	s_add_u32 s0, s34, s0
	s_addc_u32 s1, s35, s1
	v_mov_b32_e32 v2, 1
	v_mov_b64_e32 v[0:1], s[0:1]
	s_waitcnt vmcnt(0) lgkmcnt(0)
	s_nop 0
	flat_atomic_add v[0:1], v2
	s_waitcnt vmcnt(0)

.LBB0_1286:
	s_lshl_b32 s20, s33, 6
	s_add_i32 s2, s20, 0x500
	s_mov_b32 s3, 0
	s_lshl_b64 s[0:1], s[2:3], 2
	s_add_u32 s0, s34, s0
	s_addc_u32 s1, s35, s1
	v_mov_b32_e32 v1, 1
	v_mov_b64_e32 v[4:5], s[0:1]
	flat_atomic_add v1, v[4:5], v1 sc0
	v_cvt_f32_u32_e32 v3, v2
	v_sub_u32_e32 v4, 0, v2
	v_rcp_iflag_f32_e32 v3, v3
	s_nop 0
	v_mul_f32_e32 v3, 0x4f7ffffe, v3
	v_cvt_u32_f32_e32 v3, v3
	v_mul_lo_u32 v4, v4, v3
	v_mul_hi_u32 v4, v3, v4
	v_add_u32_e32 v3, v3, v4
	s_waitcnt vmcnt(0) lgkmcnt(0)
	v_mul_hi_u32 v3, v1, v3
	v_mul_lo_u32 v5, v3, v2
	v_add_u32_e32 v4, 1, v1
	v_sub_u32_e32 v1, v1, v5
	v_add_u32_e32 v6, 1, v3
	v_cmp_ge_u32_e32 vcc, v1, v2
	v_sub_u32_e32 v5, v1, v2
	s_nop 0
	v_cndmask_b32_e32 v3, v3, v6, vcc
	v_cndmask_b32_e32 v1, v1, v5, vcc
	v_add_u32_e32 v5, 1, v3
	v_cmp_ge_u32_e32 vcc, v1, v2
	s_nop 1
	v_cndmask_b32_e32 v1, v3, v5, vcc
	v_mad_u64_u32 v[2:3], s[0:1], v2, v1, v[2:3]
	v_cmp_ne_u32_e32 vcc, v4, v2
	s_and_saveexec_b64 s[0:1], vcc
	s_xor_b64 s[0:1], exec, s[0:1]
	s_cbranch_execz .LBB0_1299
	buffer_inv sc1
	s_add_i32 s2, s20, 0x900
	s_lshl_b64 s[2:3], s[2:3], 2
	s_add_u32 s4, s34, s2
	s_addc_u32 s5, s35, s3
	v_mov_b64_e32 v[2:3], s[4:5]
	flat_load_dword v0, v[2:3] sc1
	s_waitcnt vmcnt(0) lgkmcnt(0)
	v_cmp_eq_u32_e32 vcc, v0, v1
	s_and_saveexec_b64 s[2:3], vcc
	s_cbranch_execz .LBB0_1298
	s_mov_b32 s21, 1
	s_mov_b64 s[6:7], 0
	s_branch .LBB0_1290

.LBB0_1299:
	s_andn2_saveexec_b64 s[0:1], s[0:1]
	s_cbranch_execz .LBB0_1315
	v_mov_b32_e32 v1, s34
	v_add_co_u32_e32 v2, vcc, 0x3000, v1
	v_mov_b32_e32 v1, s35
	buffer_wbl2 sc1
	s_waitcnt vmcnt(0)
	buffer_inv sc1
	v_addc_co_u32_e32 v3, vcc, 0, v1, vcc
	v_mov_b32_e32 v1, 1
	flat_atomic_add v1, v[2:3], v1 offset:1024 sc0
	v_cvt_f32_u32_e32 v2, v0
	v_sub_u32_e32 v3, 0, v0
	s_add_u32 s0, s34, 0x3500
	s_addc_u32 s1, s35, 0
	v_rcp_iflag_f32_e32 v2, v2
	s_mov_b64 s[4:5], -1
	v_mul_f32_e32 v2, 0x4f7ffffe, v2
	v_cvt_u32_f32_e32 v2, v2
	v_mul_lo_u32 v3, v3, v2
	v_mul_hi_u32 v3, v2, v3
	v_add_u32_e32 v2, v2, v3
	s_waitcnt vmcnt(0) lgkmcnt(0)
	v_mul_hi_u32 v2, v1, v2
	v_mul_lo_u32 v4, v2, v0
	v_add_u32_e32 v3, 1, v1
	v_sub_u32_e32 v1, v1, v4
	v_add_u32_e32 v5, 1, v2
	v_cmp_ge_u32_e32 vcc, v1, v0
	v_sub_u32_e32 v4, v1, v0
	s_nop 0
	v_cndmask_b32_e32 v2, v2, v5, vcc
	v_cndmask_b32_e32 v1, v1, v4, vcc
	v_add_u32_e32 v4, 1, v2
	v_cmp_ge_u32_e32 vcc, v1, v0
	s_nop 1
	v_cndmask_b32_e32 v2, v2, v4, vcc
	v_mad_u64_u32 v[0:1], s[2:3], v0, v2, v[0:1]
	v_cmp_ne_u32_e32 vcc, v3, v0
	v_mov_b64_e32 v[0:1], s[0:1]
	s_and_saveexec_b64 s[2:3], vcc
	s_cbranch_execz .LBB0_1312
	v_mov_b64_e32 v[0:1], s[0:1]
	flat_load_dword v0, v[0:1] sc1
	s_mov_b64 s[8:9], 0
	s_waitcnt vmcnt(0) lgkmcnt(0)
	v_cmp_eq_u32_e32 vcc, v0, v2
	s_and_saveexec_b64 s[6:7], vcc
	s_cbranch_execz .LBB0_1311
	s_add_u32 s4, s34, 0x200
	s_addc_u32 s5, s35, 0
	s_mov_b32 s21, 1
	s_branch .LBB0_1304

.LBB0_1559:
	s_lshl_b32 s20, s33, 6
	s_add_i32 s2, s20, 0x500
	s_mov_b32 s3, 0
	s_lshl_b64 s[0:1], s[2:3], 2
	s_add_u32 s0, s38, s0
	s_addc_u32 s1, s39, s1
	v_mov_b32_e32 v1, 1
	v_mov_b64_e32 v[4:5], s[0:1]
	flat_atomic_add v1, v[4:5], v1 sc0
	v_cvt_f32_u32_e32 v3, v2
	v_sub_u32_e32 v4, 0, v2
	v_rcp_iflag_f32_e32 v3, v3
	s_nop 0
	v_mul_f32_e32 v3, 0x4f7ffffe, v3
	v_cvt_u32_f32_e32 v3, v3
	v_mul_lo_u32 v4, v4, v3
	v_mul_hi_u32 v4, v3, v4
	v_add_u32_e32 v3, v3, v4
	s_waitcnt vmcnt(0) lgkmcnt(0)
	v_mul_hi_u32 v3, v1, v3
	v_mul_lo_u32 v5, v3, v2
	v_add_u32_e32 v4, 1, v1
	v_sub_u32_e32 v1, v1, v5
	v_add_u32_e32 v6, 1, v3
	v_cmp_ge_u32_e32 vcc, v1, v2
	v_sub_u32_e32 v5, v1, v2
	s_nop 0
	v_cndmask_b32_e32 v3, v3, v6, vcc
	v_cndmask_b32_e32 v1, v1, v5, vcc
	v_add_u32_e32 v5, 1, v3
	v_cmp_ge_u32_e32 vcc, v1, v2
	s_nop 1
	v_cndmask_b32_e32 v1, v3, v5, vcc
	v_mad_u64_u32 v[2:3], s[0:1], v2, v1, v[2:3]
	v_cmp_ne_u32_e32 vcc, v4, v2
	s_and_saveexec_b64 s[0:1], vcc
	s_xor_b64 s[0:1], exec, s[0:1]
	s_cbranch_execz .LBB0_1572
	buffer_inv sc1
	s_add_i32 s2, s20, 0x900
	s_lshl_b64 s[2:3], s[2:3], 2
	s_add_u32 s4, s38, s2
	s_addc_u32 s5, s39, s3
	v_mov_b64_e32 v[2:3], s[4:5]
	flat_load_dword v0, v[2:3] sc1
	s_waitcnt vmcnt(0) lgkmcnt(0)
	v_cmp_eq_u32_e32 vcc, v0, v1
	s_and_saveexec_b64 s[2:3], vcc
	s_cbranch_execz .LBB0_1571
	s_mov_b32 s21, 1
	s_mov_b64 s[6:7], 0
	s_branch .LBB0_1563

.LBB0_1572:
	s_andn2_saveexec_b64 s[0:1], s[0:1]
	s_cbranch_execz .LBB0_1588
	v_mov_b32_e32 v1, s38
	v_add_co_u32_e32 v2, vcc, 0x3000, v1
	v_mov_b32_e32 v1, s39
	buffer_wbl2 sc1
	s_waitcnt vmcnt(0)
	buffer_inv sc1
	v_addc_co_u32_e32 v3, vcc, 0, v1, vcc
	v_mov_b32_e32 v1, 1
	flat_atomic_add v1, v[2:3], v1 offset:1024 sc0
	v_cvt_f32_u32_e32 v2, v0
	v_sub_u32_e32 v3, 0, v0
	s_add_u32 s0, s38, 0x3500
	s_addc_u32 s1, s39, 0
	v_rcp_iflag_f32_e32 v2, v2
	s_mov_b64 s[4:5], -1
	v_mul_f32_e32 v2, 0x4f7ffffe, v2
	v_cvt_u32_f32_e32 v2, v2
	v_mul_lo_u32 v3, v3, v2
	v_mul_hi_u32 v3, v2, v3
	v_add_u32_e32 v2, v2, v3
	s_waitcnt vmcnt(0) lgkmcnt(0)
	v_mul_hi_u32 v2, v1, v2
	v_mul_lo_u32 v4, v2, v0
	v_add_u32_e32 v3, 1, v1
	v_sub_u32_e32 v1, v1, v4
	v_add_u32_e32 v5, 1, v2
	v_cmp_ge_u32_e32 vcc, v1, v0
	v_sub_u32_e32 v4, v1, v0
	s_nop 0
	v_cndmask_b32_e32 v2, v2, v5, vcc
	v_cndmask_b32_e32 v1, v1, v4, vcc
	v_add_u32_e32 v4, 1, v2
	v_cmp_ge_u32_e32 vcc, v1, v0
	s_nop 1
	v_cndmask_b32_e32 v2, v2, v4, vcc
	v_mad_u64_u32 v[0:1], s[2:3], v0, v2, v[0:1]
	v_cmp_ne_u32_e32 vcc, v3, v0
	v_mov_b64_e32 v[0:1], s[0:1]
	s_and_saveexec_b64 s[2:3], vcc
	s_cbranch_execz .LBB0_1585
	v_mov_b64_e32 v[0:1], s[0:1]
	flat_load_dword v0, v[0:1] sc1
	s_mov_b64 s[8:9], 0
	s_waitcnt vmcnt(0) lgkmcnt(0)
	v_cmp_eq_u32_e32 vcc, v0, v2
	s_and_saveexec_b64 s[6:7], vcc
	s_cbranch_execz .LBB0_1584
	s_add_u32 s4, s38, 0x200
	s_addc_u32 s5, s39, 0
	s_mov_b32 s21, 1
	s_branch .LBB0_1577

.LBB0_1587:
	s_or_b64 exec, exec, s[0:1]
	s_add_i32 s0, s20, 0x900
	s_mov_b32 s1, 0
	s_lshl_b64 s[0:1], s[0:1], 2
	s_add_u32 s0, s38, s0
	s_addc_u32 s1, s39, s1
	v_mov_b32_e32 v2, 1
	v_mov_b64_e32 v[0:1], s[0:1]
	s_waitcnt vmcnt(0) lgkmcnt(0)
	s_nop 0
	flat_atomic_add v[0:1], v2
	s_waitcnt vmcnt(0)

.LBB0_1679:
	s_lshl_b32 s20, s33, 6
	s_add_i32 s2, s20, 0x500
	s_mov_b32 s3, 0
	s_lshl_b64 s[0:1], s[2:3], 2
	s_add_u32 s0, s40, s0
	s_addc_u32 s1, s41, s1
	v_mov_b32_e32 v1, 1
	v_mov_b64_e32 v[4:5], s[0:1]
	flat_atomic_add v1, v[4:5], v1 sc0
	v_cvt_f32_u32_e32 v3, v2
	v_sub_u32_e32 v4, 0, v2
	v_rcp_iflag_f32_e32 v3, v3
	s_nop 0
	v_mul_f32_e32 v3, 0x4f7ffffe, v3
	v_cvt_u32_f32_e32 v3, v3
	v_mul_lo_u32 v4, v4, v3
	v_mul_hi_u32 v4, v3, v4
	v_add_u32_e32 v3, v3, v4
	s_waitcnt vmcnt(0) lgkmcnt(0)
	v_mul_hi_u32 v3, v1, v3
	v_mul_lo_u32 v5, v3, v2
	v_add_u32_e32 v4, 1, v1
	v_sub_u32_e32 v1, v1, v5
	v_add_u32_e32 v6, 1, v3
	v_cmp_ge_u32_e32 vcc, v1, v2
	v_sub_u32_e32 v5, v1, v2
	s_nop 0
	v_cndmask_b32_e32 v3, v3, v6, vcc
	v_cndmask_b32_e32 v1, v1, v5, vcc
	v_add_u32_e32 v5, 1, v3
	v_cmp_ge_u32_e32 vcc, v1, v2
	s_nop 1
	v_cndmask_b32_e32 v1, v3, v5, vcc
	v_mad_u64_u32 v[2:3], s[0:1], v2, v1, v[2:3]
	v_cmp_ne_u32_e32 vcc, v4, v2
	s_and_saveexec_b64 s[0:1], vcc
	s_xor_b64 s[0:1], exec, s[0:1]
	s_cbranch_execz .LBB0_1692
	buffer_inv sc1
	s_add_i32 s2, s20, 0x900
	s_lshl_b64 s[2:3], s[2:3], 2
	s_add_u32 s4, s40, s2
	s_addc_u32 s5, s41, s3
	v_mov_b64_e32 v[2:3], s[4:5]
	flat_load_dword v0, v[2:3] sc1
	s_waitcnt vmcnt(0) lgkmcnt(0)
	v_cmp_eq_u32_e32 vcc, v0, v1
	s_and_saveexec_b64 s[2:3], vcc
	s_cbranch_execz .LBB0_1691
	s_mov_b32 s21, 1
	s_mov_b64 s[6:7], 0
	s_branch .LBB0_1683

.LBB0_1692:
	s_andn2_saveexec_b64 s[0:1], s[0:1]
	s_cbranch_execz .LBB0_1708
	v_mov_b32_e32 v1, s40
	v_add_co_u32_e32 v2, vcc, 0x3000, v1
	v_mov_b32_e32 v1, s41
	buffer_wbl2 sc1
	s_waitcnt vmcnt(0)
	buffer_inv sc1
	v_addc_co_u32_e32 v3, vcc, 0, v1, vcc
	v_mov_b32_e32 v1, 1
	flat_atomic_add v1, v[2:3], v1 offset:1024 sc0
	v_cvt_f32_u32_e32 v2, v0
	v_sub_u32_e32 v3, 0, v0
	s_add_u32 s0, s40, 0x3500
	s_addc_u32 s1, s41, 0
	v_rcp_iflag_f32_e32 v2, v2
	s_mov_b64 s[4:5], -1
	v_mul_f32_e32 v2, 0x4f7ffffe, v2
	v_cvt_u32_f32_e32 v2, v2
	v_mul_lo_u32 v3, v3, v2
	v_mul_hi_u32 v3, v2, v3
	v_add_u32_e32 v2, v2, v3
	s_waitcnt vmcnt(0) lgkmcnt(0)
	v_mul_hi_u32 v2, v1, v2
	v_mul_lo_u32 v4, v2, v0
	v_add_u32_e32 v3, 1, v1
	v_sub_u32_e32 v1, v1, v4
	v_add_u32_e32 v5, 1, v2
	v_cmp_ge_u32_e32 vcc, v1, v0
	v_sub_u32_e32 v4, v1, v0
	s_nop 0
	v_cndmask_b32_e32 v2, v2, v5, vcc
	v_cndmask_b32_e32 v1, v1, v4, vcc
	v_add_u32_e32 v4, 1, v2
	v_cmp_ge_u32_e32 vcc, v1, v0
	s_nop 1
	v_cndmask_b32_e32 v2, v2, v4, vcc
	v_mad_u64_u32 v[0:1], s[2:3], v0, v2, v[0:1]
	v_cmp_ne_u32_e32 vcc, v3, v0
	v_mov_b64_e32 v[0:1], s[0:1]
	s_and_saveexec_b64 s[2:3], vcc
	s_cbranch_execz .LBB0_1705
	v_mov_b64_e32 v[0:1], s[0:1]
	flat_load_dword v0, v[0:1] sc1
	s_mov_b64 s[8:9], 0
	s_waitcnt vmcnt(0) lgkmcnt(0)
	v_cmp_eq_u32_e32 vcc, v0, v2
	s_and_saveexec_b64 s[6:7], vcc
	s_cbranch_execz .LBB0_1704
	s_add_u32 s4, s40, 0x200
	s_addc_u32 s5, s41, 0
	s_mov_b32 s21, 1
	s_branch .LBB0_1697

.LBB0_1707:
	s_or_b64 exec, exec, s[0:1]
	s_add_i32 s0, s20, 0x900
	s_mov_b32 s1, 0
	s_lshl_b64 s[0:1], s[0:1], 2
	s_add_u32 s0, s40, s0
	s_addc_u32 s1, s41, s1
	v_mov_b32_e32 v2, 1
	v_mov_b64_e32 v[0:1], s[0:1]
	s_waitcnt vmcnt(0) lgkmcnt(0)
	s_nop 0
	flat_atomic_add v[0:1], v2
	s_waitcnt vmcnt(0)

.LBB0_1729:
	s_lshl_b32 s22, s33, 6
	s_add_i32 s2, s22, 0x500
	s_mov_b32 s3, 0
	s_lshl_b64 s[0:1], s[2:3], 2
	s_add_u32 s0, s42, s0
	s_addc_u32 s1, s43, s1
	v_mov_b32_e32 v1, 1
	v_mov_b64_e32 v[4:5], s[0:1]
	flat_atomic_add v1, v[4:5], v1 sc0
	v_cvt_f32_u32_e32 v3, v2
	v_sub_u32_e32 v4, 0, v2
	v_rcp_iflag_f32_e32 v3, v3
	s_nop 0
	v_mul_f32_e32 v3, 0x4f7ffffe, v3
	v_cvt_u32_f32_e32 v3, v3
	v_mul_lo_u32 v4, v4, v3
	v_mul_hi_u32 v4, v3, v4
	v_add_u32_e32 v3, v3, v4
	s_waitcnt vmcnt(0) lgkmcnt(0)
	v_mul_hi_u32 v3, v1, v3
	v_mul_lo_u32 v5, v3, v2
	v_add_u32_e32 v4, 1, v1
	v_sub_u32_e32 v1, v1, v5
	v_add_u32_e32 v6, 1, v3
	v_cmp_ge_u32_e32 vcc, v1, v2
	v_sub_u32_e32 v5, v1, v2
	s_nop 0
	v_cndmask_b32_e32 v3, v3, v6, vcc
	v_cndmask_b32_e32 v1, v1, v5, vcc
	v_add_u32_e32 v5, 1, v3
	v_cmp_ge_u32_e32 vcc, v1, v2
	s_nop 1
	v_cndmask_b32_e32 v1, v3, v5, vcc
	v_mad_u64_u32 v[2:3], s[0:1], v2, v1, v[2:3]
	v_cmp_ne_u32_e32 vcc, v4, v2
	s_and_saveexec_b64 s[0:1], vcc
	s_xor_b64 s[0:1], exec, s[0:1]
	s_cbranch_execz .LBB0_1742
	buffer_inv sc1
	s_add_i32 s2, s22, 0x900
	s_lshl_b64 s[2:3], s[2:3], 2
	s_add_u32 s4, s42, s2
	s_addc_u32 s5, s43, s3
	v_mov_b64_e32 v[2:3], s[4:5]
	flat_load_dword v0, v[2:3] sc1
	s_waitcnt vmcnt(0) lgkmcnt(0)
	v_cmp_eq_u32_e32 vcc, v0, v1
	s_and_saveexec_b64 s[2:3], vcc
	s_cbranch_execz .LBB0_1741
	s_mov_b32 s23, 1
	s_mov_b64 s[8:9], 0
	s_branch .LBB0_1733

.LBB0_1742:
	s_andn2_saveexec_b64 s[0:1], s[0:1]
	s_cbranch_execz .LBB0_1758
	v_mov_b32_e32 v1, s42
	v_add_co_u32_e32 v2, vcc, 0x3000, v1
	v_mov_b32_e32 v1, s43
	buffer_wbl2 sc1
	s_waitcnt vmcnt(0)
	buffer_inv sc1
	v_addc_co_u32_e32 v3, vcc, 0, v1, vcc
	v_mov_b32_e32 v1, 1
	flat_atomic_add v1, v[2:3], v1 offset:1024 sc0
	v_cvt_f32_u32_e32 v2, v0
	v_sub_u32_e32 v3, 0, v0
	s_add_u32 s0, s42, 0x3500
	s_addc_u32 s1, s43, 0
	v_rcp_iflag_f32_e32 v2, v2
	s_mov_b64 s[4:5], -1
	v_mul_f32_e32 v2, 0x4f7ffffe, v2
	v_cvt_u32_f32_e32 v2, v2
	v_mul_lo_u32 v3, v3, v2
	v_mul_hi_u32 v3, v2, v3
	v_add_u32_e32 v2, v2, v3
	s_waitcnt vmcnt(0) lgkmcnt(0)
	v_mul_hi_u32 v2, v1, v2
	v_mul_lo_u32 v4, v2, v0
	v_add_u32_e32 v3, 1, v1
	v_sub_u32_e32 v1, v1, v4
	v_add_u32_e32 v5, 1, v2
	v_cmp_ge_u32_e32 vcc, v1, v0
	v_sub_u32_e32 v4, v1, v0
	s_nop 0
	v_cndmask_b32_e32 v2, v2, v5, vcc
	v_cndmask_b32_e32 v1, v1, v4, vcc
	v_add_u32_e32 v4, 1, v2
	v_cmp_ge_u32_e32 vcc, v1, v0
	s_nop 1
	v_cndmask_b32_e32 v2, v2, v4, vcc
	v_mad_u64_u32 v[0:1], s[2:3], v0, v2, v[0:1]
	v_cmp_ne_u32_e32 vcc, v3, v0
	v_mov_b64_e32 v[0:1], s[0:1]
	s_and_saveexec_b64 s[2:3], vcc
	s_cbranch_execz .LBB0_1755
	v_mov_b64_e32 v[0:1], s[0:1]
	flat_load_dword v0, v[0:1] sc1
	s_mov_b64 s[10:11], 0
	s_waitcnt vmcnt(0) lgkmcnt(0)
	v_cmp_eq_u32_e32 vcc, v0, v2
	s_and_saveexec_b64 s[8:9], vcc
	s_cbranch_execz .LBB0_1754
	s_add_u32 s4, s42, 0x200
	s_addc_u32 s5, s43, 0
	s_mov_b32 s23, 1
	s_branch .LBB0_1747

.LBB0_1757:
	s_or_b64 exec, exec, s[0:1]
	s_add_i32 s0, s22, 0x900
	s_mov_b32 s1, 0
	s_lshl_b64 s[0:1], s[0:1], 2
	s_add_u32 s0, s42, s0
	s_addc_u32 s1, s43, s1
	v_mov_b32_e32 v2, 1
	v_mov_b64_e32 v[0:1], s[0:1]
	s_waitcnt vmcnt(0) lgkmcnt(0)
	s_nop 0
	flat_atomic_add v[0:1], v2
	s_waitcnt vmcnt(0)

.LBB0_1801:
	s_lshl_b32 s22, s33, 6
	s_add_i32 s2, s22, 0x500
	s_mov_b32 s3, 0
	s_lshl_b64 s[0:1], s[2:3], 2
	s_add_u32 s0, s40, s0
	s_addc_u32 s1, s41, s1
	v_mov_b32_e32 v1, 1
	v_mov_b64_e32 v[4:5], s[0:1]
	flat_atomic_add v1, v[4:5], v1 sc0
	v_cvt_f32_u32_e32 v3, v2
	v_sub_u32_e32 v4, 0, v2
	v_rcp_iflag_f32_e32 v3, v3
	s_nop 0
	v_mul_f32_e32 v3, 0x4f7ffffe, v3
	v_cvt_u32_f32_e32 v3, v3
	v_mul_lo_u32 v4, v4, v3
	v_mul_hi_u32 v4, v3, v4
	v_add_u32_e32 v3, v3, v4
	s_waitcnt vmcnt(0) lgkmcnt(0)
	v_mul_hi_u32 v3, v1, v3
	v_mul_lo_u32 v5, v3, v2
	v_add_u32_e32 v4, 1, v1
	v_sub_u32_e32 v1, v1, v5
	v_add_u32_e32 v6, 1, v3
	v_cmp_ge_u32_e32 vcc, v1, v2
	v_sub_u32_e32 v5, v1, v2
	s_nop 0
	v_cndmask_b32_e32 v3, v3, v6, vcc
	v_cndmask_b32_e32 v1, v1, v5, vcc
	v_add_u32_e32 v5, 1, v3
	v_cmp_ge_u32_e32 vcc, v1, v2
	s_nop 1
	v_cndmask_b32_e32 v1, v3, v5, vcc
	v_mad_u64_u32 v[2:3], s[0:1], v2, v1, v[2:3]
	v_cmp_ne_u32_e32 vcc, v4, v2
	s_and_saveexec_b64 s[0:1], vcc
	s_xor_b64 s[0:1], exec, s[0:1]
	s_cbranch_execz .LBB0_1814
	buffer_inv sc1
	s_add_i32 s2, s22, 0x900
	s_lshl_b64 s[2:3], s[2:3], 2
	s_add_u32 s4, s40, s2
	s_addc_u32 s5, s41, s3
	v_mov_b64_e32 v[2:3], s[4:5]
	flat_load_dword v0, v[2:3] sc1
	s_waitcnt vmcnt(0) lgkmcnt(0)
	v_cmp_eq_u32_e32 vcc, v0, v1
	s_and_saveexec_b64 s[2:3], vcc
	s_cbranch_execz .LBB0_1813
	s_mov_b32 s23, 1
	s_mov_b64 s[8:9], 0
	s_branch .LBB0_1805

.LBB0_1814:
	s_andn2_saveexec_b64 s[0:1], s[0:1]
	s_cbranch_execz .LBB0_1830
	v_mov_b32_e32 v1, s40
	v_add_co_u32_e32 v2, vcc, 0x3000, v1
	v_mov_b32_e32 v1, s41
	buffer_wbl2 sc1
	s_waitcnt vmcnt(0)
	buffer_inv sc1
	v_addc_co_u32_e32 v3, vcc, 0, v1, vcc
	v_mov_b32_e32 v1, 1
	flat_atomic_add v1, v[2:3], v1 offset:1024 sc0
	v_cvt_f32_u32_e32 v2, v0
	v_sub_u32_e32 v3, 0, v0
	s_add_u32 s0, s40, 0x3500
	s_addc_u32 s1, s41, 0
	v_rcp_iflag_f32_e32 v2, v2
	s_mov_b64 s[4:5], -1
	v_mul_f32_e32 v2, 0x4f7ffffe, v2
	v_cvt_u32_f32_e32 v2, v2
	v_mul_lo_u32 v3, v3, v2
	v_mul_hi_u32 v3, v2, v3
	v_add_u32_e32 v2, v2, v3
	s_waitcnt vmcnt(0) lgkmcnt(0)
	v_mul_hi_u32 v2, v1, v2
	v_mul_lo_u32 v4, v2, v0
	v_add_u32_e32 v3, 1, v1
	v_sub_u32_e32 v1, v1, v4
	v_add_u32_e32 v5, 1, v2
	v_cmp_ge_u32_e32 vcc, v1, v0
	v_sub_u32_e32 v4, v1, v0
	s_nop 0
	v_cndmask_b32_e32 v2, v2, v5, vcc
	v_cndmask_b32_e32 v1, v1, v4, vcc
	v_add_u32_e32 v4, 1, v2
	v_cmp_ge_u32_e32 vcc, v1, v0
	s_nop 1
	v_cndmask_b32_e32 v2, v2, v4, vcc
	v_mad_u64_u32 v[0:1], s[2:3], v0, v2, v[0:1]
	v_cmp_ne_u32_e32 vcc, v3, v0
	v_mov_b64_e32 v[0:1], s[0:1]
	s_and_saveexec_b64 s[2:3], vcc
	s_cbranch_execz .LBB0_1827
	v_mov_b64_e32 v[0:1], s[0:1]
	flat_load_dword v0, v[0:1] sc1
	s_mov_b64 s[10:11], 0
	s_waitcnt vmcnt(0) lgkmcnt(0)
	v_cmp_eq_u32_e32 vcc, v0, v2
	s_and_saveexec_b64 s[8:9], vcc
	s_cbranch_execz .LBB0_1826
	s_add_u32 s4, s40, 0x200
	s_addc_u32 s5, s41, 0
	s_mov_b32 s23, 1
	s_branch .LBB0_1819

.LBB0_1829:
	s_or_b64 exec, exec, s[0:1]
	s_add_i32 s0, s22, 0x900
	s_mov_b32 s1, 0
	s_lshl_b64 s[0:1], s[0:1], 2
	s_add_u32 s0, s40, s0
	s_addc_u32 s1, s41, s1
	v_mov_b32_e32 v2, 1
	v_mov_b64_e32 v[0:1], s[0:1]
	s_waitcnt vmcnt(0) lgkmcnt(0)
	s_nop 0
	flat_atomic_add v[0:1], v2
	s_waitcnt vmcnt(0)

.LBB0_1921:
	s_lshl_b32 s22, s91, 6
	s_add_i32 s2, s22, 0x500
	s_mov_b32 s3, 0
	s_lshl_b64 s[0:1], s[2:3], 2
	s_add_u32 s0, s76, s0
	s_addc_u32 s1, s77, s1
	v_mov_b32_e32 v1, 1
	v_mov_b64_e32 v[4:5], s[0:1]
	flat_atomic_add v1, v[4:5], v1 sc0
	v_cvt_f32_u32_e32 v3, v2
	v_sub_u32_e32 v4, 0, v2
	v_rcp_iflag_f32_e32 v3, v3
	s_nop 0
	v_mul_f32_e32 v3, 0x4f7ffffe, v3
	v_cvt_u32_f32_e32 v3, v3
	v_mul_lo_u32 v4, v4, v3
	v_mul_hi_u32 v4, v3, v4
	v_add_u32_e32 v3, v3, v4
	s_waitcnt vmcnt(0) lgkmcnt(0)
	v_mul_hi_u32 v3, v1, v3
	v_mul_lo_u32 v5, v3, v2
	v_add_u32_e32 v4, 1, v1
	v_sub_u32_e32 v1, v1, v5
	v_add_u32_e32 v6, 1, v3
	v_cmp_ge_u32_e32 vcc, v1, v2
	v_sub_u32_e32 v5, v1, v2
	s_nop 0
	v_cndmask_b32_e32 v3, v3, v6, vcc
	v_cndmask_b32_e32 v1, v1, v5, vcc
	v_add_u32_e32 v5, 1, v3
	v_cmp_ge_u32_e32 vcc, v1, v2
	s_nop 1
	v_cndmask_b32_e32 v1, v3, v5, vcc
	v_mad_u64_u32 v[2:3], s[0:1], v2, v1, v[2:3]
	v_cmp_ne_u32_e32 vcc, v4, v2
	s_and_saveexec_b64 s[0:1], vcc
	s_xor_b64 s[0:1], exec, s[0:1]
	s_cbranch_execz .LBB0_1934
	buffer_inv sc1
	s_add_i32 s2, s22, 0x900
	s_lshl_b64 s[2:3], s[2:3], 2
	s_add_u32 s4, s76, s2
	s_addc_u32 s5, s77, s3
	v_mov_b64_e32 v[2:3], s[4:5]
	flat_load_dword v0, v[2:3] sc1
	s_waitcnt vmcnt(0) lgkmcnt(0)
	v_cmp_eq_u32_e32 vcc, v0, v1
	s_and_saveexec_b64 s[2:3], vcc
	s_cbranch_execz .LBB0_1933
	s_mov_b32 s23, 1
	s_mov_b64 s[8:9], 0
	s_branch .LBB0_1925

.LBB0_1934:
	s_andn2_saveexec_b64 s[0:1], s[0:1]
	s_cbranch_execz .LBB0_1950
	v_mov_b32_e32 v1, s76
	v_add_co_u32_e32 v2, vcc, 0x3000, v1
	v_mov_b32_e32 v1, s77
	buffer_wbl2 sc1
	s_waitcnt vmcnt(0)
	buffer_inv sc1
	v_addc_co_u32_e32 v3, vcc, 0, v1, vcc
	v_mov_b32_e32 v1, 1
	flat_atomic_add v1, v[2:3], v1 offset:1024 sc0
	v_cvt_f32_u32_e32 v2, v0
	v_sub_u32_e32 v3, 0, v0
	s_add_u32 s0, s76, 0x3500
	s_addc_u32 s1, s77, 0
	v_rcp_iflag_f32_e32 v2, v2
	s_mov_b64 s[4:5], -1
	v_mul_f32_e32 v2, 0x4f7ffffe, v2
	v_cvt_u32_f32_e32 v2, v2
	v_mul_lo_u32 v3, v3, v2
	v_mul_hi_u32 v3, v2, v3
	v_add_u32_e32 v2, v2, v3
	s_waitcnt vmcnt(0) lgkmcnt(0)
	v_mul_hi_u32 v2, v1, v2
	v_mul_lo_u32 v4, v2, v0
	v_add_u32_e32 v3, 1, v1
	v_sub_u32_e32 v1, v1, v4
	v_add_u32_e32 v5, 1, v2
	v_cmp_ge_u32_e32 vcc, v1, v0
	v_sub_u32_e32 v4, v1, v0
	s_nop 0
	v_cndmask_b32_e32 v2, v2, v5, vcc
	v_cndmask_b32_e32 v1, v1, v4, vcc
	v_add_u32_e32 v4, 1, v2
	v_cmp_ge_u32_e32 vcc, v1, v0
	s_nop 1
	v_cndmask_b32_e32 v2, v2, v4, vcc
	v_mad_u64_u32 v[0:1], s[2:3], v0, v2, v[0:1]
	v_cmp_ne_u32_e32 vcc, v3, v0
	v_mov_b64_e32 v[0:1], s[0:1]
	s_and_saveexec_b64 s[2:3], vcc
	s_cbranch_execz .LBB0_1947
	v_mov_b64_e32 v[0:1], s[0:1]
	flat_load_dword v0, v[0:1] sc1
	s_mov_b64 s[10:11], 0
	s_waitcnt vmcnt(0) lgkmcnt(0)
	v_cmp_eq_u32_e32 vcc, v0, v2
	s_and_saveexec_b64 s[8:9], vcc
	s_cbranch_execz .LBB0_1946
	s_add_u32 s4, s76, 0x200
	s_addc_u32 s5, s77, 0
	s_mov_b32 s23, 1
	s_branch .LBB0_1939

.LBB0_1949:
	s_or_b64 exec, exec, s[0:1]
	s_add_i32 s0, s22, 0x900
	s_mov_b32 s1, 0
	s_lshl_b64 s[0:1], s[0:1], 2
	s_add_u32 s0, s76, s0
	s_addc_u32 s1, s77, s1
	v_mov_b32_e32 v2, 1
	v_mov_b64_e32 v[0:1], s[0:1]
	s_waitcnt vmcnt(0) lgkmcnt(0)
	s_nop 0
	flat_atomic_add v[0:1], v2
	s_waitcnt vmcnt(0)

	.amdhsa_kernel _Z9hymba_fwd6Params
		.amdhsa_group_segment_fixed_size 0
		.amdhsa_private_segment_fixed_size 0
		.amdhsa_kernarg_size 552
		.amdhsa_user_sgpr_count 2
		.amdhsa_user_sgpr_dispatch_ptr 0
		.amdhsa_user_sgpr_queue_ptr 0
		.amdhsa_user_sgpr_kernarg_segment_ptr 1
		.amdhsa_user_sgpr_dispatch_id 0
		.amdhsa_user_sgpr_kernarg_preload_length 0
		.amdhsa_user_sgpr_kernarg_preload_offset 0
		.amdhsa_user_sgpr_private_segment_size 0
		.amdhsa_uses_dynamic_stack 0
		.amdhsa_enable_private_segment 0
		.amdhsa_system_sgpr_workgroup_id_x 1
		.amdhsa_system_sgpr_workgroup_id_y 0
		.amdhsa_system_sgpr_workgroup_id_z 0
		.amdhsa_system_sgpr_workgroup_info 0
		.amdhsa_system_vgpr_workitem_id 2
		.amdhsa_next_free_vgpr 256
		.amdhsa_next_free_sgpr 102
		.amdhsa_accum_offset 256
		.amdhsa_reserve_vcc 1
		.amdhsa_float_round_mode_32 0
		.amdhsa_float_round_mode_16_64 0
		.amdhsa_float_denorm_mode_32 3
		.amdhsa_float_denorm_mode_16_64 3
		.amdhsa_dx10_clamp 1
		.amdhsa_ieee_mode 1
		.amdhsa_fp16_overflow 0
		.amdhsa_tg_split 0
		.amdhsa_exception_fp_ieee_invalid_op 0
		.amdhsa_exception_fp_denorm_src 0
		.amdhsa_exception_fp_ieee_div_zero 0
		.amdhsa_exception_fp_ieee_overflow 0
		.amdhsa_exception_fp_ieee_underflow 0
		.amdhsa_exception_fp_ieee_inexact 0
		.amdhsa_exception_int_div_zero 0
	.end_amdhsa_kernel

amdhsa.kernels:
  - .agpr_count:     0
    .args:
      - .offset:         0
        .size:           296
        .value_kind:     by_value
      - .offset:         296
        .size:           4
        .value_kind:     hidden_block_count_x
      - .offset:         300
        .size:           4
        .value_kind:     hidden_block_count_y
      - .offset:         304
        .size:           4
        .value_kind:     hidden_block_count_z
      - .offset:         308
        .size:           2
        .value_kind:     hidden_group_size_x
      - .offset:         310
        .size:           2
        .value_kind:     hidden_group_size_y
      - .offset:         312
        .size:           2
        .value_kind:     hidden_group_size_z
      - .offset:         314
        .size:           2
        .value_kind:     hidden_remainder_x
      - .offset:         316
        .size:           2
        .value_kind:     hidden_remainder_y
      - .offset:         318
        .size:           2
        .value_kind:     hidden_remainder_z
      - .offset:         336
        .size:           8
        .value_kind:     hidden_global_offset_x
      - .offset:         344
        .size:           8
        .value_kind:     hidden_global_offset_y
      - .offset:         352
        .size:           8
        .value_kind:     hidden_global_offset_z
      - .offset:         360
        .size:           2
        .value_kind:     hidden_grid_dims
      - .offset:         384
        .size:           8
        .value_kind:     hidden_multigrid_sync_arg
      - .offset:         416
        .size:           4
        .value_kind:     hidden_dynamic_lds_size
    .group_segment_fixed_size: 0
    .kernarg_segment_align: 8
    .kernarg_segment_size: 552
    .language:       OpenCL C
    .language_version:
      - 2
      - 0
    .max_flat_workgroup_size: 512
    .name:           _Z9hymba_fwd6Params
    .private_segment_fixed_size: 0
    .sgpr_count:     108
    .sgpr_spill_count: 299
    .symbol:         _Z9hymba_fwd6Params.kd
    .uniform_work_group_size: 1
    .uses_dynamic_stack: false
    .vgpr_count:     256
    .vgpr_spill_count: 0
    .wavefront_size: 64
